# FFN1 epilogue: ds_bpermute lane reductions (xor16/xor32) replaced by v_permlane16/32_swap (bit-identical); on top of final combined
# speedup vs baseline: 1.0132x; 1.0047x over previous
; __device__ __forceinline__ float fast_sigmoid(float v) { return __builtin_amdgcn_rcpf(1.0f + __builtin_amdgcn_exp2f(-1.4426950408889634f * v)); }
; __device__ __forceinline__ u32x4 pack8(const float* v) { u32x4 w; w.x = cvt_pk_bf16(v[0], v[1]); w.y = cvt_pk_bf16(v[2], v[3]); w.z = cvt_pk_bf16(v[4], v[5]); w.w = cvt_pk_bf16(v[6], v[7]); return w; }
;     __device__ __forceinline__ void operator()(int row, int pn, int within, const float* a, const float* b, float) const { (void)apply(row, pn, within, a, b); }
;     __device__ __forceinline__ void operator()(int row, int pn, int within, const float* a, const float* b, float) const { Pre p = preload(row, pn, within, 0); finish(row, pn, within, a, b, p); }
; #define PG8_GATHER(ai, m) float a[8], b[8]; _Pragma("unroll") for (int j = 0; j < 4; ++j) { a[j] = acc[ai][0][m][0][j]; a[4 + j] = acc[ai][0][m][1][j]; b[j] = acc[ai][1][m][0][j]; b[4 + j] = acc[ai][1][m][1][j]; }
;     __device__ __forceinline__ void finish(int row, int pn, int within, const float* a, const float* b, const Pre& p) const {
;         const f32x4 s4 = p.s0 + p.s1; float sm = (s4[0] + s4[1]) + (s4[2] + s4[3]); sm += __shfl_xor(sm, 16); sm += __shfl_xor(sm, 32);
;         (*this)(row, pn, within, a, b, __builtin_amdgcn_rsqf(sm * (1.0f / DM) + EPS)); }
;     __device__ __forceinline__ void operator()(int row, int pn, int within, const float* a, const float* b, float rc) const {
;         float o[8];
; #pragma unroll
;         for (int j = 0; j < 8; ++j) { const float g = a[j] * rc, u = b[j] * rc; o[j] = g * fast_sigmoid(g) * u; }
;         *(u32x4*)(hidden + (size_t)row * DFF + pn * 128 + within) = pack8(o);
; template <class Epi> __device__ __forceinline__ void run_epi(const Epi& E, const f32x4 (&acc)[2][2][4][2], const Unit& u, int wr, int wc, int fr, int fq) {
;     ...
;     const int within = wc * 32 + fq * 8;
; #pragma unroll
;     for (int ai = 0; ai < 2; ++ai) { const int row0 = u.pm * BM + ai * HALF + wr * 64 + fr; typename Epi::Pre pre[4];
; #pragma unroll
;         for (int m = 0; m < 4; ++m) pre[m] = E.preload(row0 + m * 16, u.pn, within, fq);
; #pragma unroll
;         for (int m = 0; m < 4; ++m) { PG8_GATHER(ai, m); E.finish(row0 + m * 16, u.pn, within, a, b, pre[m]); } }
.LBB0_599:
	s_lshl_b32 s17, s24, 8
	v_mov_b32_e32 v128, v165
	v_mov_b32_e32 v129, v164
	s_add_i32 s17, s17, s44
	s_lshl_b32 s24, s25, 7
	v_lshlrev_b32_e32 v158, 3, v128
	v_add_u32_e32 v154, s17, v129
	v_ashrrev_i32_e32 v159, 31, v158
	v_ashrrev_i32_e32 v155, 31, v154
	v_lshl_add_u64 v[156:157], v[158:159], 2, s[8:9]
	v_lshlrev_b64 v[128:129], 7, v[154:155]
	v_lshl_add_u64 v[132:133], v[156:157], 0, v[128:129]
	global_load_dwordx4 v[128:131], v[132:133], off
	s_nop 0
	global_load_dwordx4 v[132:135], v[132:133], off offset:16
	v_add_u32_e32 v160, 16, v154
	v_ashrrev_i32_e32 v161, 31, v160
	v_lshlrev_b64 v[152:153], 7, v[160:161]
	v_lshl_add_u64 v[152:153], v[156:157], 0, v[152:153]
	global_load_dwordx4 v[172:175], v[152:153], off
	global_load_dwordx4 v[176:179], v[152:153], off offset:16
	v_and_b32_e32 v159, 64, v170
	v_xor_b32_e32 v155, 16, v170
	v_add_u32_e32 v159, 64, v159
	v_xor_b32_e32 v161, 32, v170
	v_cmp_lt_i32_e32 vcc, v155, v159
	v_add_u32_e32 v162, 32, v154
	v_add_u32_e32 v188, s45, v158
	v_cndmask_b32_e32 v155, v170, v155, vcc
	v_cmp_lt_i32_e32 vcc, v161, v159
	v_add_u32_e32 v158, 48, v154
	v_ashrrev_i32_e32 v163, 31, v162
	v_cndmask_b32_e32 v159, v170, v161, vcc
	v_lshlrev_b32_e32 v161, 2, v155
	v_lshlrev_b32_e32 v155, 2, v159
	v_ashrrev_i32_e32 v159, 31, v158
	v_lshlrev_b64 v[180:181], 7, v[162:163]
	v_lshlrev_b64 v[182:183], 7, v[158:159]
	v_lshl_add_u64 v[184:185], v[156:157], 0, v[180:181]
	v_lshl_add_u64 v[190:191], v[156:157], 0, v[182:183]
	global_load_dwordx4 v[180:183], v[184:185], off
	s_nop 0
	global_load_dwordx4 v[184:187], v[184:185], off offset:16
	v_mov_b64_e32 v[152:153], s[10:11]
	s_ashr_i32 s25, s24, 31
	v_ashrrev_i32_e32 v189, 31, v188
	s_lshl_b64 s[24:25], s[24:25], 1
	s_andn2_b64 vcc, exec, s[0:1]
	s_mov_b64 s[0:1], -1
	s_waitcnt vmcnt(0)
	v_pk_add_f32 v[130:131], v[130:131], v[134:135]
	v_pk_add_f32 v[128:129], v[128:129], v[132:133]
	s_nop 0
	v_pk_mov_b32 v[132:133], v[128:129], v[130:131] op_sel:[1,0]
	v_mov_b32_e32 v129, v131
	v_pk_add_f32 v[128:129], v[132:133], v[128:129]
	v_pk_add_f32 v[130:131], v[172:173], v[176:177]
	v_add_f32_e32 v134, v128, v129
	v_mov_b32_e32 v135, v134
	s_nop 1
	v_permlane16_swap_b32_e32 v135, v134
	v_pk_add_f32 v[128:129], v[174:175], v[178:179]
	s_waitcnt lgkmcnt(0)
	v_add_f32_e32 v134, v134, v135
	v_mov_b32_e32 v135, v134
	s_nop 1
	v_permlane32_swap_b32_e32 v135, v134
	v_pk_mov_b32 v[132:133], v[130:131], v[128:129] op_sel:[1,0]
	v_mov_b32_e32 v131, v129
	v_pk_add_f32 v[128:129], v[132:133], v[130:131]
	s_nop 0
	v_add_f32_e32 v159, v128, v129
	s_waitcnt lgkmcnt(0)
	v_add_f32_e32 v128, v134, v135
	v_fmamk_f32 v128, v128, 0x3a000000, v171
	v_rsq_f32_e32 v172, v128
	v_mov_b32_e32 v163, v159
	s_nop 1
	v_permlane16_swap_b32_e32 v163, v159
	global_load_dwordx4 v[128:131], v[190:191], off
	global_load_dwordx4 v[132:135], v[190:191], off offset:16
	v_pk_mul_f32 v[126:127], v[126:127], v[172:173] op_sel_hi:[1,0]
	v_pk_mul_f32 v[120:121], v[120:121], v[172:173] op_sel_hi:[1,0]
	v_pk_mul_f32 v[122:123], v[122:123], v[172:173] op_sel_hi:[1,0]
	v_mul_f32_e32 v174, 0xbfb8aa3b, v126
	v_mul_f32_e32 v175, 0xbfb8aa3b, v127
	v_mul_f32_e32 v176, 0xbfb8aa3b, v120
	v_mul_f32_e32 v177, 0xbfb8aa3b, v121
	v_mul_f32_e32 v178, 0xbfb8aa3b, v122
	v_mul_f32_e32 v179, 0xbfb8aa3b, v123
	v_exp_f32_e32 v174, v174
	v_exp_f32_e32 v175, v175
	v_exp_f32_e32 v176, v176
	v_exp_f32_e32 v177, v177
	v_exp_f32_e32 v178, v178
	v_exp_f32_e32 v179, v179
	v_add_f32_e32 v174, 1.0, v174
	v_add_f32_e32 v175, 1.0, v175
	s_waitcnt lgkmcnt(0)
	v_add_f32_e32 v159, v159, v163
	v_add_f32_e32 v176, 1.0, v176
	v_add_f32_e32 v177, 1.0, v177
	v_add_f32_e32 v178, 1.0, v178
	v_add_f32_e32 v179, 1.0, v179
	v_rcp_f32_e32 v174, v174
	v_rcp_f32_e32 v175, v175
	v_mov_b32_e32 v163, v159
	s_nop 1
	v_permlane32_swap_b32_e32 v163, v159
	v_rcp_f32_e32 v176, v176
	v_rcp_f32_e32 v177, v177
	v_rcp_f32_e32 v178, v178
	v_rcp_f32_e32 v179, v179
	v_pk_mul_f32 v[124:125], v[124:125], v[172:173] op_sel_hi:[1,0]
	v_pk_mul_f32 v[116:117], v[116:117], v[172:173] op_sel_hi:[1,0]
	v_pk_mul_f32 v[118:119], v[118:119], v[172:173] op_sel_hi:[1,0]
	v_pk_mul_f32 v[112:113], v[112:113], v[172:173] op_sel_hi:[1,0]
	v_pk_mul_f32 v[114:115], v[114:115], v[172:173] op_sel_hi:[1,0]
	v_mul_f32_e32 v172, 0xbfb8aa3b, v124
	v_mul_f32_e32 v173, 0xbfb8aa3b, v125
	v_exp_f32_e32 v172, v172
	v_exp_f32_e32 v173, v173
	v_pk_mul_f32 v[126:127], v[126:127], v[174:175]
	v_pk_mul_f32 v[120:121], v[120:121], v[176:177]
	v_pk_mul_f32 v[122:123], v[122:123], v[178:179]
	v_pk_mul_f32 v[118:119], v[118:119], v[126:127]
	v_pk_mul_f32 v[112:113], v[112:113], v[120:121]
	v_pk_mul_f32 v[120:121], v[114:115], v[122:123]
	v_cvt_pk_bf16_f32 v115, v118, v119
	s_waitcnt lgkmcnt(0)
; __device__ __forceinline__ float fast_sigmoid(float v) { return __builtin_amdgcn_rcpf(1.0f + __builtin_amdgcn_exp2f(-1.4426950408889634f * v)); }
; __device__ __forceinline__ u32x4 pack8(const float* v) { u32x4 w; w.x = cvt_pk_bf16(v[0], v[1]); w.y = cvt_pk_bf16(v[2], v[3]); w.z = cvt_pk_bf16(v[4], v[5]); w.w = cvt_pk_bf16(v[6], v[7]); return w; }
;     __device__ __forceinline__ void operator()(int row, int pn, int within, const float* a, const float* b, float) const { (void)apply(row, pn, within, a, b); }
;     __device__ __forceinline__ void operator()(int row, int pn, int within, const float* a, const float* b, float) const { Pre p = preload(row, pn, within, 0); finish(row, pn, within, a, b, p); }
;     __device__ __forceinline__ void finish(int row, int pn, int within, const float* a, const float* b, const Pre& p) const {
;         const f32x4 s4 = p.s0 + p.s1; float sm = (s4[0] + s4[1]) + (s4[2] + s4[3]); sm += __shfl_xor(sm, 16); sm += __shfl_xor(sm, 32);
;         (*this)(row, pn, within, a, b, __builtin_amdgcn_rsqf(sm * (1.0f / DM) + EPS)); }
;     __device__ __forceinline__ void operator()(int row, int pn, int within, const float* a, const float* b, float rc) const {
;         float o[8];
; #pragma unroll
;         for (int j = 0; j < 8; ++j) { const float g = a[j] * rc, u = b[j] * rc; o[j] = g * fast_sigmoid(g) * u; }
;         *(u32x4*)(hidden + (size_t)row * DFF + pn * 128 + within) = pack8(o);
	v_add_f32_e32 v118, v159, v163
	v_fmamk_f32 v118, v118, 0x3a000000, v171
	v_add_f32_e32 v172, 1.0, v172
	v_add_f32_e32 v173, 1.0, v173
	v_rsq_f32_e32 v118, v118
	v_rcp_f32_e32 v172, v172
	v_rcp_f32_e32 v173, v173
	v_pk_mul_f32 v[108:109], v[108:109], v[118:119] op_sel_hi:[1,0]
	s_nop 0
	v_mul_f32_e32 v119, 0xbfb8aa3b, v108
	v_pk_mul_f32 v[124:125], v[124:125], v[172:173]
	v_exp_f32_e32 v119, v119
	v_pk_mul_f32 v[116:117], v[116:117], v[124:125]
	v_pk_mul_f32 v[110:111], v[110:111], v[118:119] op_sel_hi:[1,0]
	v_cvt_pk_bf16_f32 v114, v116, v117
	v_cvt_pk_bf16_f32 v116, v112, v113
	v_mad_i64_i32 v[112:113], s[26:27], v154, s52, v[152:153]
	v_cvt_pk_bf16_f32 v117, v120, v121
	v_lshl_add_u64 v[120:121], v[112:113], 0, s[24:25]
	v_lshlrev_b64 v[112:113], 1, v[188:189]
	v_lshl_add_u64 v[120:121], v[120:121], 0, v[112:113]
	global_store_dwordx4 v[120:121], v[114:117], off
	v_pk_mul_f32 v[100:101], v[100:101], v[118:119] op_sel_hi:[1,0]
	v_pk_mul_f32 v[102:103], v[102:103], v[118:119] op_sel_hi:[1,0]
	v_mul_f32_e32 v114, 0xbfb8aa3b, v109
	v_exp_f32_e32 v115, v114
	v_mul_f32_e32 v116, 0xbfb8aa3b, v110
	v_mul_f32_e32 v117, 0xbfb8aa3b, v111
	v_exp_f32_e32 v116, v116
	v_exp_f32_e32 v117, v117
	v_add_f32_e32 v114, 1.0, v119
	v_add_f32_e32 v115, 1.0, v115
	v_rcp_f32_e32 v114, v114
	v_rcp_f32_e32 v115, v115
	v_add_f32_e32 v116, 1.0, v116
	v_add_f32_e32 v117, 1.0, v117
	v_rcp_f32_e32 v116, v116
	v_rcp_f32_e32 v117, v117
	v_pk_mul_f32 v[108:109], v[108:109], v[114:115]
	v_pk_mul_f32 v[104:105], v[104:105], v[118:119] op_sel_hi:[1,0]
	v_pk_mul_f32 v[100:101], v[100:101], v[108:109]
	v_pk_mul_f32 v[108:109], v[110:111], v[116:117]
	v_mul_f32_e32 v110, 0xbfb8aa3b, v104
	v_pk_mul_f32 v[102:103], v[102:103], v[108:109]
	v_mul_f32_e32 v108, 0xbfb8aa3b, v105
	v_exp_f32_e32 v110, v110
	v_exp_f32_e32 v109, v108
	v_pk_mul_f32 v[106:107], v[106:107], v[118:119] op_sel_hi:[1,0]
	v_pk_add_f32 v[114:115], v[180:181], v[184:185]
	v_add_f32_e32 v108, 1.0, v110
	v_add_f32_e32 v109, 1.0, v109
	v_mul_f32_e32 v110, 0xbfb8aa3b, v106
	v_mul_f32_e32 v111, 0xbfb8aa3b, v107
	v_rcp_f32_e32 v108, v108
	v_rcp_f32_e32 v109, v109
	v_exp_f32_e32 v110, v110
	v_exp_f32_e32 v111, v111
	v_pk_mul_f32 v[96:97], v[96:97], v[118:119] op_sel_hi:[1,0]
	v_pk_mul_f32 v[104:105], v[104:105], v[108:109]
	v_add_f32_e32 v108, 1.0, v110
	v_add_f32_e32 v109, 1.0, v111
	v_pk_add_f32 v[110:111], v[182:183], v[186:187]
	v_rcp_f32_e32 v108, v108
	v_pk_mov_b32 v[116:117], v[114:115], v[110:111] op_sel:[1,0]
	v_mov_b32_e32 v115, v111
	v_pk_add_f32 v[110:111], v[116:117], v[114:115]
	v_rcp_f32_e32 v109, v109
	v_add_f32_e32 v110, v110, v111
	v_mov_b32_e32 v111, v110
	s_nop 1
	v_permlane16_swap_b32_e32 v111, v110
	v_pk_mul_f32 v[104:105], v[96:97], v[104:105]
	v_pk_mul_f32 v[96:97], v[98:99], v[118:119] op_sel_hi:[1,0]
	v_pk_mul_f32 v[98:99], v[106:107], v[108:109]
	s_waitcnt lgkmcnt(0)
	v_add_f32_e32 v108, v110, v111
	v_mov_b32_e32 v109, v108
	s_nop 1
	v_permlane32_swap_b32_e32 v109, v108
	v_pk_mul_f32 v[106:107], v[96:97], v[98:99]
	v_cvt_pk_bf16_f32 v96, v100, v101
	v_cvt_pk_bf16_f32 v97, v102, v103
	v_mad_i64_i32 v[102:103], s[26:27], v160, s52, v[152:153]
	s_waitcnt lgkmcnt(0)
	v_add_f32_e32 v100, v108, v109
	v_fmamk_f32 v100, v100, 0x3a000000, v171
	v_rsq_f32_e32 v100, v100
	v_lshl_add_u64 v[102:103], v[102:103], 0, s[24:25]
	v_cvt_pk_bf16_f32 v98, v104, v105
	v_cvt_pk_bf16_f32 v99, v106, v107
	v_pk_mul_f32 v[92:93], v[92:93], v[100:101] op_sel_hi:[1,0]
	v_lshl_add_u64 v[102:103], v[102:103], 0, v[112:113]
	v_mul_f32_e32 v101, 0xbfb8aa3b, v92
	v_exp_f32_e32 v101, v101
	global_store_dwordx4 v[102:103], v[96:99], off
	v_pk_mul_f32 v[94:95], v[94:95], v[100:101] op_sel_hi:[1,0]
	s_nop 0
	v_mul_f32_e32 v96, 0xbfb8aa3b, v93
	v_exp_f32_e32 v97, v96
	v_mul_f32_e32 v98, 0xbfb8aa3b, v94
	v_mul_f32_e32 v99, 0xbfb8aa3b, v95
	v_exp_f32_e32 v98, v98
	v_exp_f32_e32 v99, v99
	v_add_f32_e32 v96, 1.0, v101
	v_add_f32_e32 v97, 1.0, v97
	v_rcp_f32_e32 v96, v96
	v_rcp_f32_e32 v97, v97
	v_add_f32_e32 v98, 1.0, v98
	v_add_f32_e32 v99, 1.0, v99
	v_rcp_f32_e32 v98, v98
	v_rcp_f32_e32 v99, v99
	v_pk_mul_f32 v[84:85], v[84:85], v[100:101] op_sel_hi:[1,0]
	v_pk_mul_f32 v[92:93], v[92:93], v[96:97]
	v_pk_mul_f32 v[86:87], v[86:87], v[100:101] op_sel_hi:[1,0]
	v_pk_mul_f32 v[84:85], v[84:85], v[92:93]
	v_pk_mul_f32 v[92:93], v[94:95], v[98:99]
	v_pk_mul_f32 v[88:89], v[88:89], v[100:101] op_sel_hi:[1,0]
	v_pk_mul_f32 v[86:87], v[86:87], v[92:93]
	v_mul_f32_e32 v94, 0xbfb8aa3b, v88
	v_mul_f32_e32 v92, 0xbfb8aa3b, v89
	v_exp_f32_e32 v94, v94
	v_exp_f32_e32 v93, v92
	v_pk_mul_f32 v[90:91], v[90:91], v[100:101] op_sel_hi:[1,0]
	s_waitcnt vmcnt(2)
	v_pk_add_f32 v[96:97], v[128:129], v[132:133]
	v_add_f32_e32 v92, 1.0, v94
	v_add_f32_e32 v93, 1.0, v93
	v_mul_f32_e32 v94, 0xbfb8aa3b, v90
	v_mul_f32_e32 v95, 0xbfb8aa3b, v91
	v_rcp_f32_e32 v92, v92
	v_rcp_f32_e32 v93, v93
	v_exp_f32_e32 v94, v94
	v_exp_f32_e32 v95, v95
	v_pk_mul_f32 v[80:81], v[80:81], v[100:101] op_sel_hi:[1,0]
	v_pk_mul_f32 v[88:89], v[88:89], v[92:93]
	v_add_f32_e32 v92, 1.0, v94
	v_add_f32_e32 v93, 1.0, v95
	v_pk_add_f32 v[94:95], v[130:131], v[134:135]
	v_rcp_f32_e32 v92, v92
	v_pk_mov_b32 v[98:99], v[96:97], v[94:95] op_sel:[1,0]
	v_mov_b32_e32 v97, v95
	v_pk_add_f32 v[94:95], v[98:99], v[96:97]
	v_rcp_f32_e32 v93, v93
	v_add_f32_e32 v94, v94, v95
	v_mov_b32_e32 v95, v94
	s_nop 1
	v_permlane16_swap_b32_e32 v95, v94
	v_pk_mul_f32 v[88:89], v[80:81], v[88:89]
	v_pk_mul_f32 v[80:81], v[82:83], v[100:101] op_sel_hi:[1,0]
	v_pk_mul_f32 v[82:83], v[90:91], v[92:93]
	s_waitcnt lgkmcnt(0)
; __device__ __forceinline__ float fast_sigmoid(float v) { return __builtin_amdgcn_rcpf(1.0f + __builtin_amdgcn_exp2f(-1.4426950408889634f * v)); }
; __device__ __forceinline__ u32x4 pack8(const float* v) { u32x4 w; w.x = cvt_pk_bf16(v[0], v[1]); w.y = cvt_pk_bf16(v[2], v[3]); w.z = cvt_pk_bf16(v[4], v[5]); w.w = cvt_pk_bf16(v[6], v[7]); return w; }
;     __device__ __forceinline__ void operator()(int row, int pn, int within, const float* a, const float* b, float) const { (void)apply(row, pn, within, a, b); }
;     __device__ __forceinline__ void operator()(int row, int pn, int within, const float* a, const float* b, float) const { Pre p = preload(row, pn, within, 0); finish(row, pn, within, a, b, p); }
;     __device__ __forceinline__ void finish(int row, int pn, int within, const float* a, const float* b, const Pre& p) const {
;         const f32x4 s4 = p.s0 + p.s1; float sm = (s4[0] + s4[1]) + (s4[2] + s4[3]); sm += __shfl_xor(sm, 16); sm += __shfl_xor(sm, 32);
;         (*this)(row, pn, within, a, b, __builtin_amdgcn_rsqf(sm * (1.0f / DM) + EPS)); }
;     __device__ __forceinline__ void operator()(int row, int pn, int within, const float* a, const float* b, float rc) const {
;         float o[8];
; #pragma unroll
;         for (int j = 0; j < 8; ++j) { const float g = a[j] * rc, u = b[j] * rc; o[j] = g * fast_sigmoid(g) * u; }
;         *(u32x4*)(hidden + (size_t)row * DFF + pn * 128 + within) = pack8(o);
	v_add_f32_e32 v92, v94, v95
	v_mov_b32_e32 v93, v92
	s_nop 1
	v_permlane32_swap_b32_e32 v93, v92
	v_pk_mul_f32 v[90:91], v[80:81], v[82:83]
	v_cvt_pk_bf16_f32 v80, v84, v85
	v_cvt_pk_bf16_f32 v81, v86, v87
	v_mad_i64_i32 v[86:87], s[26:27], v162, s52, v[152:153]
	s_waitcnt lgkmcnt(0)
	v_add_f32_e32 v84, v92, v93
	v_fmamk_f32 v84, v84, 0x3a000000, v171
	v_rsq_f32_e32 v84, v84
	v_lshl_add_u64 v[86:87], v[86:87], 0, s[24:25]
	v_cvt_pk_bf16_f32 v82, v88, v89
	v_cvt_pk_bf16_f32 v83, v90, v91
	v_pk_mul_f32 v[76:77], v[76:77], v[84:85] op_sel_hi:[1,0]
	v_lshl_add_u64 v[86:87], v[86:87], 0, v[112:113]
	v_mul_f32_e32 v85, 0xbfb8aa3b, v76
	v_exp_f32_e32 v85, v85
	global_store_dwordx4 v[86:87], v[80:83], off
	v_add_u32_e32 v94, 0x80, v154
	v_ashrrev_i32_e32 v95, 31, v94
	v_mul_f32_e32 v80, 0xbfb8aa3b, v77
	v_pk_mul_f32 v[78:79], v[78:79], v[84:85] op_sel_hi:[1,0]
	v_exp_f32_e32 v81, v80
	v_mul_f32_e32 v82, 0xbfb8aa3b, v78
	v_mul_f32_e32 v83, 0xbfb8aa3b, v79
	v_exp_f32_e32 v82, v82
	v_exp_f32_e32 v83, v83
	v_add_f32_e32 v80, 1.0, v85
	v_add_f32_e32 v81, 1.0, v81
	v_rcp_f32_e32 v80, v80
	v_rcp_f32_e32 v81, v81
	v_add_f32_e32 v82, 1.0, v82
	v_add_f32_e32 v83, 1.0, v83
	v_rcp_f32_e32 v82, v82
	v_rcp_f32_e32 v83, v83
	v_pk_mul_f32 v[68:69], v[68:69], v[84:85] op_sel_hi:[1,0]
	v_pk_mul_f32 v[76:77], v[76:77], v[80:81]
	v_pk_mul_f32 v[72:73], v[72:73], v[84:85] op_sel_hi:[1,0]
	v_pk_mul_f32 v[68:69], v[68:69], v[76:77]
	v_pk_mul_f32 v[76:77], v[78:79], v[82:83]
	v_mul_f32_e32 v78, 0xbfb8aa3b, v72
	v_exp_f32_e32 v78, v78
	v_pk_mul_f32 v[70:71], v[70:71], v[84:85] op_sel_hi:[1,0]
	v_pk_mul_f32 v[74:75], v[74:75], v[84:85] op_sel_hi:[1,0]
	v_pk_mul_f32 v[70:71], v[70:71], v[76:77]
	v_mul_f32_e32 v76, 0xbfb8aa3b, v73
	v_exp_f32_e32 v77, v76
	v_add_f32_e32 v76, 1.0, v78
	v_mul_f32_e32 v78, 0xbfb8aa3b, v74
	v_mul_f32_e32 v79, 0xbfb8aa3b, v75
	v_exp_f32_e32 v78, v78
	v_exp_f32_e32 v79, v79
	v_add_f32_e32 v77, 1.0, v77
	v_rcp_f32_e32 v76, v76
	v_rcp_f32_e32 v77, v77
	v_add_f32_e32 v78, 1.0, v78
	v_add_f32_e32 v79, 1.0, v79
	v_rcp_f32_e32 v78, v78
	v_rcp_f32_e32 v79, v79
	v_pk_mul_f32 v[64:65], v[64:65], v[84:85] op_sel_hi:[1,0]
	v_pk_mul_f32 v[72:73], v[72:73], v[76:77]
	v_add_u32_e32 v76, 0x90, v154
	v_pk_mul_f32 v[72:73], v[64:65], v[72:73]
	v_pk_mul_f32 v[64:65], v[66:67], v[84:85] op_sel_hi:[1,0]
	v_pk_mul_f32 v[66:67], v[74:75], v[78:79]
	v_ashrrev_i32_e32 v77, 31, v76
	v_pk_mul_f32 v[74:75], v[64:65], v[66:67]
	v_cvt_pk_bf16_f32 v64, v68, v69
	v_mad_i64_i32 v[68:69], s[26:27], v158, s52, v[152:153]
	v_lshl_add_u64 v[68:69], v[68:69], 0, s[24:25]
	v_cvt_pk_bf16_f32 v65, v70, v71
	v_cvt_pk_bf16_f32 v66, v72, v73
	v_cvt_pk_bf16_f32 v67, v74, v75
	v_lshl_add_u64 v[68:69], v[68:69], 0, v[112:113]
	global_store_dwordx4 v[68:69], v[64:67], off
	v_lshlrev_b64 v[72:73], 7, v[76:77]
	v_lshl_add_u64 v[72:73], v[156:157], 0, v[72:73]
	v_lshlrev_b64 v[64:65], 7, v[94:95]
	v_lshl_add_u64 v[68:69], v[156:157], 0, v[64:65]
	global_load_dwordx4 v[64:67], v[68:69], off
	s_nop 0
	global_load_dwordx4 v[68:71], v[68:69], off offset:16
	s_nop 0
	global_load_dwordx4 v[78:81], v[72:73], off
	global_load_dwordx4 v[82:85], v[72:73], off offset:16
	v_add_u32_e32 v74, 0xa0, v154
	v_ashrrev_i32_e32 v75, 31, v74
	v_add_u32_e32 v72, 0xb0, v154
	v_ashrrev_i32_e32 v73, 31, v72
	s_waitcnt vmcnt(2)
	v_pk_add_f32 v[66:67], v[66:67], v[70:71]
	v_pk_add_f32 v[64:65], v[64:65], v[68:69]
	s_waitcnt vmcnt(0)
	v_pk_add_f32 v[78:79], v[78:79], v[82:83]
	v_pk_mov_b32 v[68:69], v[64:65], v[66:67] op_sel:[1,0]
	v_mov_b32_e32 v65, v67
	v_pk_add_f32 v[64:65], v[68:69], v[64:65]
	s_nop 0
	v_add_f32_e32 v66, v64, v65
	v_mov_b32_e32 v67, v66
	s_nop 1
	v_permlane16_swap_b32_e32 v67, v66
	v_lshlrev_b64 v[64:65], 7, v[74:75]
	v_lshl_add_u64 v[64:65], v[156:157], 0, v[64:65]
	global_load_dwordx4 v[86:89], v[64:65], off
	global_load_dwordx4 v[90:93], v[64:65], off offset:16
	s_waitcnt lgkmcnt(0)
	v_add_f32_e32 v66, v66, v67
	v_mov_b32_e32 v67, v66
	s_nop 1
	v_permlane32_swap_b32_e32 v67, v66
	s_waitcnt lgkmcnt(0)
	v_add_f32_e32 v64, v66, v67
	v_fmamk_f32 v64, v64, 0x3a000000, v171
	v_rsq_f32_e32 v96, v64
	v_lshlrev_b64 v[64:65], 7, v[72:73]
	v_lshl_add_u64 v[68:69], v[156:157], 0, v[64:65]
	v_pk_mul_f32 v[60:61], v[60:61], v[96:97] op_sel_hi:[1,0]
	s_nop 0
	v_mul_f32_e32 v64, 0xbfb8aa3b, v60
	v_exp_f32_e32 v73, v64
	v_mul_f32_e32 v75, 0xbfb8aa3b, v61
	v_exp_f32_e32 v75, v75
	v_pk_mul_f32 v[62:63], v[62:63], v[96:97] op_sel_hi:[1,0]
	v_add_f32_e32 v73, 1.0, v73
	v_rcp_f32_e32 v98, v73
	v_add_f32_e32 v73, 1.0, v75
	v_mul_f32_e32 v75, 0xbfb8aa3b, v62
	v_exp_f32_e32 v75, v75
	v_mul_f32_e32 v77, 0xbfb8aa3b, v63
	v_exp_f32_e32 v77, v77
	v_rcp_f32_e32 v99, v73
	v_add_f32_e32 v73, 1.0, v75
	v_rcp_f32_e32 v100, v73
	v_add_f32_e32 v73, 1.0, v77
	v_rcp_f32_e32 v101, v73
	v_pk_mul_f32 v[52:53], v[52:53], v[96:97] op_sel_hi:[1,0]
	v_pk_mul_f32 v[60:61], v[60:61], v[98:99]
	v_pk_mul_f32 v[54:55], v[54:55], v[96:97] op_sel_hi:[1,0]
	v_pk_mul_f32 v[52:53], v[52:53], v[60:61]
	v_pk_mul_f32 v[60:61], v[62:63], v[100:101]
	v_pk_mul_f32 v[56:57], v[56:57], v[96:97] op_sel_hi:[1,0]
	v_pk_mul_f32 v[54:55], v[54:55], v[60:61]
	v_mul_f32_e32 v62, 0xbfb8aa3b, v56
	v_mul_f32_e32 v60, 0xbfb8aa3b, v57
	v_exp_f32_e32 v62, v62
	v_exp_f32_e32 v61, v60
	v_pk_mul_f32 v[58:59], v[58:59], v[96:97] op_sel_hi:[1,0]
	v_pk_mul_f32 v[48:49], v[48:49], v[96:97] op_sel_hi:[1,0]
	v_add_f32_e32 v60, 1.0, v62
	v_add_f32_e32 v61, 1.0, v61
	v_mul_f32_e32 v62, 0xbfb8aa3b, v58
	v_mul_f32_e32 v63, 0xbfb8aa3b, v59
	v_rcp_f32_e32 v60, v60
	v_rcp_f32_e32 v61, v61
	v_exp_f32_e32 v62, v62
	v_exp_f32_e32 v63, v63
	global_load_dwordx4 v[64:67], v[68:69], off
	s_nop 0
	global_load_dwordx4 v[68:71], v[68:69], off offset:16
	v_pk_mul_f32 v[56:57], v[56:57], v[60:61]
	v_add_f32_e32 v60, 1.0, v62
	v_add_f32_e32 v61, 1.0, v63
	v_pk_add_f32 v[62:63], v[80:81], v[84:85]
	v_rcp_f32_e32 v60, v60
	v_pk_mov_b32 v[80:81], v[78:79], v[62:63] op_sel:[1,0]
	v_mov_b32_e32 v79, v63
	v_pk_add_f32 v[62:63], v[80:81], v[78:79]
	v_rcp_f32_e32 v61, v61
	v_add_f32_e32 v62, v62, v63
	v_mov_b32_e32 v63, v62
	s_nop 1
	v_permlane16_swap_b32_e32 v63, v62
	v_pk_mul_f32 v[56:57], v[48:49], v[56:57]
	v_pk_mul_f32 v[48:49], v[50:51], v[96:97] op_sel_hi:[1,0]
	v_pk_mul_f32 v[50:51], v[58:59], v[60:61]
	s_waitcnt lgkmcnt(0)
; __device__ __forceinline__ float fast_sigmoid(float v) { return __builtin_amdgcn_rcpf(1.0f + __builtin_amdgcn_exp2f(-1.4426950408889634f * v)); }
; __device__ __forceinline__ u32x4 pack8(const float* v) { u32x4 w; w.x = cvt_pk_bf16(v[0], v[1]); w.y = cvt_pk_bf16(v[2], v[3]); w.z = cvt_pk_bf16(v[4], v[5]); w.w = cvt_pk_bf16(v[6], v[7]); return w; }
;     __device__ __forceinline__ void operator()(int row, int pn, int within, const float* a, const float* b, float) const { (void)apply(row, pn, within, a, b); }
;     __device__ __forceinline__ void operator()(int row, int pn, int within, const float* a, const float* b, float) const { Pre p = preload(row, pn, within, 0); finish(row, pn, within, a, b, p); }
;     __device__ __forceinline__ void finish(int row, int pn, int within, const float* a, const float* b, const Pre& p) const {
;         const f32x4 s4 = p.s0 + p.s1; float sm = (s4[0] + s4[1]) + (s4[2] + s4[3]); sm += __shfl_xor(sm, 16); sm += __shfl_xor(sm, 32);
;         (*this)(row, pn, within, a, b, __builtin_amdgcn_rsqf(sm * (1.0f / DM) + EPS)); }
;     __device__ __forceinline__ void operator()(int row, int pn, int within, const float* a, const float* b, float rc) const {
;         float o[8];
; #pragma unroll
;         for (int j = 0; j < 8; ++j) { const float g = a[j] * rc, u = b[j] * rc; o[j] = g * fast_sigmoid(g) * u; }
;         *(u32x4*)(hidden + (size_t)row * DFF + pn * 128 + within) = pack8(o);
	v_add_f32_e32 v60, v62, v63
	v_mov_b32_e32 v61, v60
	s_nop 1
	v_permlane32_swap_b32_e32 v61, v60
	v_pk_mul_f32 v[58:59], v[48:49], v[50:51]
	v_cvt_pk_bf16_f32 v48, v52, v53
	v_cvt_pk_bf16_f32 v49, v54, v55
	v_mad_i64_i32 v[54:55], s[26:27], v94, s52, v[152:153]
	s_waitcnt lgkmcnt(0)
	v_add_f32_e32 v52, v60, v61
	v_fmamk_f32 v52, v52, 0x3a000000, v171
	v_rsq_f32_e32 v52, v52
	v_lshl_add_u64 v[54:55], v[54:55], 0, s[24:25]
	v_cvt_pk_bf16_f32 v50, v56, v57
	v_cvt_pk_bf16_f32 v51, v58, v59
	v_pk_mul_f32 v[44:45], v[44:45], v[52:53] op_sel_hi:[1,0]
	v_lshl_add_u64 v[54:55], v[54:55], 0, v[112:113]
	v_mul_f32_e32 v53, 0xbfb8aa3b, v44
	v_exp_f32_e32 v53, v53
	global_store_dwordx4 v[54:55], v[48:51], off
	v_pk_mul_f32 v[46:47], v[46:47], v[52:53] op_sel_hi:[1,0]
	s_nop 0
	v_mul_f32_e32 v48, 0xbfb8aa3b, v45
	v_exp_f32_e32 v49, v48
	v_mul_f32_e32 v50, 0xbfb8aa3b, v46
	v_mul_f32_e32 v51, 0xbfb8aa3b, v47
	v_exp_f32_e32 v50, v50
	v_exp_f32_e32 v51, v51
	v_add_f32_e32 v48, 1.0, v53
	v_add_f32_e32 v49, 1.0, v49
	v_rcp_f32_e32 v48, v48
	v_rcp_f32_e32 v49, v49
	v_add_f32_e32 v50, 1.0, v50
	v_add_f32_e32 v51, 1.0, v51
	v_rcp_f32_e32 v50, v50
	v_rcp_f32_e32 v51, v51
	v_pk_mul_f32 v[36:37], v[36:37], v[52:53] op_sel_hi:[1,0]
	v_pk_mul_f32 v[44:45], v[44:45], v[48:49]
	v_pk_mul_f32 v[38:39], v[38:39], v[52:53] op_sel_hi:[1,0]
	v_pk_mul_f32 v[36:37], v[36:37], v[44:45]
	v_pk_mul_f32 v[44:45], v[46:47], v[50:51]
	v_pk_mul_f32 v[40:41], v[40:41], v[52:53] op_sel_hi:[1,0]
	v_pk_mul_f32 v[38:39], v[38:39], v[44:45]
	v_mul_f32_e32 v46, 0xbfb8aa3b, v40
	v_mul_f32_e32 v44, 0xbfb8aa3b, v41
	v_exp_f32_e32 v46, v46
	v_exp_f32_e32 v45, v44
	v_pk_mul_f32 v[42:43], v[42:43], v[52:53] op_sel_hi:[1,0]
	s_waitcnt vmcnt(3)
	v_pk_add_f32 v[48:49], v[86:87], v[90:91]
	v_add_f32_e32 v44, 1.0, v46
	v_add_f32_e32 v45, 1.0, v45
	v_mul_f32_e32 v46, 0xbfb8aa3b, v42
	v_mul_f32_e32 v47, 0xbfb8aa3b, v43
	v_rcp_f32_e32 v44, v44
	v_rcp_f32_e32 v45, v45
	v_exp_f32_e32 v46, v46
	v_exp_f32_e32 v47, v47
	v_pk_mul_f32 v[32:33], v[32:33], v[52:53] op_sel_hi:[1,0]
	v_pk_mul_f32 v[40:41], v[40:41], v[44:45]
	v_add_f32_e32 v44, 1.0, v46
	v_add_f32_e32 v45, 1.0, v47
	v_pk_add_f32 v[46:47], v[88:89], v[92:93]
	v_rcp_f32_e32 v44, v44
	v_pk_mov_b32 v[50:51], v[48:49], v[46:47] op_sel:[1,0]
	v_mov_b32_e32 v49, v47
	v_pk_add_f32 v[46:47], v[50:51], v[48:49]
	v_rcp_f32_e32 v45, v45
	v_add_f32_e32 v46, v46, v47
	v_mov_b32_e32 v47, v46
	s_nop 1
	v_permlane16_swap_b32_e32 v47, v46
	v_pk_mul_f32 v[40:41], v[32:33], v[40:41]
	v_pk_mul_f32 v[32:33], v[34:35], v[52:53] op_sel_hi:[1,0]
	v_pk_mul_f32 v[34:35], v[42:43], v[44:45]
	s_waitcnt lgkmcnt(0)
	v_add_f32_e32 v44, v46, v47
	v_mov_b32_e32 v45, v44
	s_nop 1
	v_permlane32_swap_b32_e32 v45, v44
	v_pk_mul_f32 v[42:43], v[32:33], v[34:35]
	v_cvt_pk_bf16_f32 v32, v36, v37
	v_cvt_pk_bf16_f32 v33, v38, v39
	v_mad_i64_i32 v[38:39], s[26:27], v76, s52, v[152:153]
	s_waitcnt lgkmcnt(0)
	v_add_f32_e32 v36, v44, v45
	v_fmamk_f32 v36, v36, 0x3a000000, v171
	v_rsq_f32_e32 v36, v36
	v_lshl_add_u64 v[38:39], v[38:39], 0, s[24:25]
	v_cvt_pk_bf16_f32 v34, v40, v41
	v_cvt_pk_bf16_f32 v35, v42, v43
	v_pk_mul_f32 v[28:29], v[28:29], v[36:37] op_sel_hi:[1,0]
	v_lshl_add_u64 v[38:39], v[38:39], 0, v[112:113]
	v_mul_f32_e32 v37, 0xbfb8aa3b, v28
	v_exp_f32_e32 v37, v37
	global_store_dwordx4 v[38:39], v[32:35], off
	v_pk_mul_f32 v[30:31], v[30:31], v[36:37] op_sel_hi:[1,0]
	s_nop 0
	v_mul_f32_e32 v32, 0xbfb8aa3b, v29
	v_exp_f32_e32 v33, v32
	v_mul_f32_e32 v34, 0xbfb8aa3b, v30
	v_mul_f32_e32 v35, 0xbfb8aa3b, v31
	v_exp_f32_e32 v34, v34
	v_exp_f32_e32 v35, v35
	v_add_f32_e32 v32, 1.0, v37
	v_add_f32_e32 v33, 1.0, v33
	v_rcp_f32_e32 v32, v32
	v_rcp_f32_e32 v33, v33
	v_add_f32_e32 v34, 1.0, v34
	v_add_f32_e32 v35, 1.0, v35
	v_rcp_f32_e32 v34, v34
	v_rcp_f32_e32 v35, v35
	v_pk_mul_f32 v[20:21], v[20:21], v[36:37] op_sel_hi:[1,0]
	v_pk_mul_f32 v[28:29], v[28:29], v[32:33]
	v_pk_mul_f32 v[22:23], v[22:23], v[36:37] op_sel_hi:[1,0]
	v_pk_mul_f32 v[20:21], v[20:21], v[28:29]
	v_pk_mul_f32 v[28:29], v[30:31], v[34:35]
	v_pk_mul_f32 v[24:25], v[24:25], v[36:37] op_sel_hi:[1,0]
	v_pk_mul_f32 v[22:23], v[22:23], v[28:29]
	v_mul_f32_e32 v30, 0xbfb8aa3b, v24
	v_mul_f32_e32 v28, 0xbfb8aa3b, v25
	v_exp_f32_e32 v30, v30
	v_exp_f32_e32 v29, v28
	v_pk_mul_f32 v[26:27], v[26:27], v[36:37] op_sel_hi:[1,0]
	s_waitcnt vmcnt(2)
; __device__ __forceinline__ float fast_sigmoid(float v) { return __builtin_amdgcn_rcpf(1.0f + __builtin_amdgcn_exp2f(-1.4426950408889634f * v)); }
; __device__ __forceinline__ u32x4 pack8(const float* v) { u32x4 w; w.x = cvt_pk_bf16(v[0], v[1]); w.y = cvt_pk_bf16(v[2], v[3]); w.z = cvt_pk_bf16(v[4], v[5]); w.w = cvt_pk_bf16(v[6], v[7]); return w; }
;     __device__ __forceinline__ void operator()(int row, int pn, int within, const float* a, const float* b, float) const { (void)apply(row, pn, within, a, b); }
;     __device__ __forceinline__ void operator()(int row, int pn, int within, const float* a, const float* b, float) const { Pre p = preload(row, pn, within, 0); finish(row, pn, within, a, b, p); }
;     __device__ __forceinline__ void finish(int row, int pn, int within, const float* a, const float* b, const Pre& p) const {
;         const f32x4 s4 = p.s0 + p.s1; float sm = (s4[0] + s4[1]) + (s4[2] + s4[3]); sm += __shfl_xor(sm, 16); sm += __shfl_xor(sm, 32);
;         (*this)(row, pn, within, a, b, __builtin_amdgcn_rsqf(sm * (1.0f / DM) + EPS)); }
;     __device__ __forceinline__ void operator()(int row, int pn, int within, const float* a, const float* b, float rc) const {
;         float o[8];
; #pragma unroll
;         for (int j = 0; j < 8; ++j) { const float g = a[j] * rc, u = b[j] * rc; o[j] = g * fast_sigmoid(g) * u; }
;         *(u32x4*)(hidden + (size_t)row * DFF + pn * 128 + within) = pack8(o);
	v_pk_add_f32 v[32:33], v[64:65], v[68:69]
	v_add_f32_e32 v28, 1.0, v30
	v_add_f32_e32 v29, 1.0, v29
	v_mul_f32_e32 v30, 0xbfb8aa3b, v26
	v_mul_f32_e32 v31, 0xbfb8aa3b, v27
	v_rcp_f32_e32 v28, v28
	v_rcp_f32_e32 v29, v29
	v_exp_f32_e32 v30, v30
	v_exp_f32_e32 v31, v31
	v_pk_mul_f32 v[16:17], v[16:17], v[36:37] op_sel_hi:[1,0]
	v_pk_mul_f32 v[24:25], v[24:25], v[28:29]
	v_add_f32_e32 v28, 1.0, v30
	v_add_f32_e32 v29, 1.0, v31
	v_pk_add_f32 v[30:31], v[66:67], v[70:71]
	v_rcp_f32_e32 v28, v28
	v_pk_mov_b32 v[34:35], v[32:33], v[30:31] op_sel:[1,0]
	v_mov_b32_e32 v33, v31
	v_pk_add_f32 v[30:31], v[34:35], v[32:33]
	v_rcp_f32_e32 v29, v29
	v_add_f32_e32 v30, v30, v31
	v_mov_b32_e32 v31, v30
	s_nop 1
	v_permlane16_swap_b32_e32 v31, v30
	v_pk_mul_f32 v[24:25], v[16:17], v[24:25]
	v_pk_mul_f32 v[16:17], v[18:19], v[36:37] op_sel_hi:[1,0]
	v_pk_mul_f32 v[18:19], v[26:27], v[28:29]
	s_waitcnt lgkmcnt(0)
	v_add_f32_e32 v28, v30, v31
	v_mov_b32_e32 v29, v28
	s_nop 1
	v_permlane32_swap_b32_e32 v29, v28
	v_pk_mul_f32 v[26:27], v[16:17], v[18:19]
	v_cvt_pk_bf16_f32 v16, v20, v21
	v_cvt_pk_bf16_f32 v17, v22, v23
	v_mad_i64_i32 v[22:23], s[26:27], v74, s52, v[152:153]
	s_waitcnt lgkmcnt(0)
	v_add_f32_e32 v20, v28, v29
	v_fmamk_f32 v20, v20, 0x3a000000, v171
	v_rsq_f32_e32 v20, v20
	v_lshl_add_u64 v[22:23], v[22:23], 0, s[24:25]
	v_cvt_pk_bf16_f32 v18, v24, v25
	v_cvt_pk_bf16_f32 v19, v26, v27
	v_pk_mul_f32 v[12:13], v[12:13], v[20:21] op_sel_hi:[1,0]
	v_lshl_add_u64 v[22:23], v[22:23], 0, v[112:113]
	v_mul_f32_e32 v21, 0xbfb8aa3b, v12
	v_exp_f32_e32 v21, v21
	global_store_dwordx4 v[22:23], v[16:19], off
	v_pk_mul_f32 v[14:15], v[14:15], v[20:21] op_sel_hi:[1,0]
	s_nop 0
	v_mul_f32_e32 v16, 0xbfb8aa3b, v13
	v_exp_f32_e32 v17, v16
	v_mul_f32_e32 v18, 0xbfb8aa3b, v14
	v_mul_f32_e32 v19, 0xbfb8aa3b, v15
	v_exp_f32_e32 v18, v18
	v_exp_f32_e32 v19, v19
	v_add_f32_e32 v16, 1.0, v21
	v_add_f32_e32 v17, 1.0, v17
	v_rcp_f32_e32 v16, v16
	v_rcp_f32_e32 v17, v17
	v_add_f32_e32 v18, 1.0, v18
	v_add_f32_e32 v19, 1.0, v19
	v_rcp_f32_e32 v18, v18
	v_rcp_f32_e32 v19, v19
	v_pk_mul_f32 v[4:5], v[4:5], v[20:21] op_sel_hi:[1,0]
	v_pk_mul_f32 v[12:13], v[12:13], v[16:17]
	v_pk_mul_f32 v[8:9], v[8:9], v[20:21] op_sel_hi:[1,0]
	v_pk_mul_f32 v[4:5], v[4:5], v[12:13]
	v_pk_mul_f32 v[12:13], v[14:15], v[18:19]
	v_mul_f32_e32 v14, 0xbfb8aa3b, v8
	v_exp_f32_e32 v14, v14
	v_pk_mul_f32 v[6:7], v[6:7], v[20:21] op_sel_hi:[1,0]
	v_pk_mul_f32 v[10:11], v[10:11], v[20:21] op_sel_hi:[1,0]
	v_pk_mul_f32 v[6:7], v[6:7], v[12:13]
	v_mul_f32_e32 v12, 0xbfb8aa3b, v9
	v_exp_f32_e32 v13, v12
	v_add_f32_e32 v12, 1.0, v14
	v_mul_f32_e32 v14, 0xbfb8aa3b, v10
	v_mul_f32_e32 v15, 0xbfb8aa3b, v11
	v_exp_f32_e32 v14, v14
	v_exp_f32_e32 v15, v15
	v_add_f32_e32 v13, 1.0, v13
	v_rcp_f32_e32 v12, v12
	v_rcp_f32_e32 v13, v13
	v_add_f32_e32 v14, 1.0, v14
	v_add_f32_e32 v15, 1.0, v15
	v_rcp_f32_e32 v14, v14
	v_rcp_f32_e32 v15, v15
	v_pk_mul_f32 v[0:1], v[0:1], v[20:21] op_sel_hi:[1,0]
	v_pk_mul_f32 v[8:9], v[8:9], v[12:13]
	s_nop 0
	v_pk_mul_f32 v[8:9], v[0:1], v[8:9]
	v_pk_mul_f32 v[0:1], v[2:3], v[20:21] op_sel_hi:[1,0]
	v_pk_mul_f32 v[2:3], v[10:11], v[14:15]
	s_nop 0
	v_pk_mul_f32 v[10:11], v[0:1], v[2:3]
	v_cvt_pk_bf16_f32 v0, v4, v5
	v_mad_i64_i32 v[4:5], s[26:27], v72, s52, v[152:153]
	v_lshl_add_u64 v[4:5], v[4:5], 0, s[24:25]
	v_cvt_pk_bf16_f32 v1, v6, v7
	v_cvt_pk_bf16_f32 v2, v8, v9
	v_cvt_pk_bf16_f32 v3, v10, v11
	v_lshl_add_u64 v[4:5], v[4:5], 0, v[112:113]
	global_store_dwordx4 v[4:5], v[0:3], off
	s_cbranch_vccnz .LBB0_592
	s_andn2_b64 vcc, exec, s[6:7]
	s_cbranch_vccnz .LBB0_591
	s_barrier
	s_branch .LBB0_591
